# best + nt (non-temporal) on the streamed f32 x / mem row loads of the P0 and P5 rmsnorm loops
# baseline (speedup 1.0000x reference)
.LBB0_94:
	v_lshlrev_b32_e32 v2, 8, v70
	v_and_b32_e32 v3, 0xff00, v31
	v_and_or_b32 v4, v2, s5, v3
	v_and_b32_e32 v34, 0x300, v70
	v_or_b32_e32 v2, v85, v4
	v_or_b32_e32 v3, v85, v34
	v_cmp_lt_u32_e64 s[8:9], s4, v70
	v_lshlrev_b32_e32 v5, 2, v2
	v_lshlrev_b32_e32 v14, 5, v3
	s_and_saveexec_b64 s[0:1], s[8:9]
	s_xor_b64 s[42:43], exec, s[0:1]
	s_cbranch_execz .LBB0_96
	v_lshl_add_u64 v[2:3], s[18:19], 0, v[14:15]
	v_add_co_u32_e32 v6, vcc, 0x10000, v2
	s_waitcnt lgkmcnt(1)
	global_load_dword v16, v5, s[16:17]
	v_addc_co_u32_e32 v7, vcc, 0, v3, vcc
	v_lshl_add_u64 v[2:3], v[2:3], 0, s[34:35]
	global_load_dwordx4 v[6:9], v[6:7], off nt
	s_nop 0
	global_load_dwordx4 v[10:13], v[2:3], off offset:16 nt
	s_waitcnt vmcnt(1)
	v_pk_fma_f32 v[6:7], v[16:17], v[6:7], 0 op_sel_hi:[0,1,0]
	v_pk_fma_f32 v[8:9], v[16:17], v[8:9], 0 op_sel_hi:[0,1,0]
	s_waitcnt vmcnt(0)
	v_pk_fma_f32 v[2:3], v[16:17], v[10:11], 0 op_sel_hi:[0,1,0]
	v_fma_f32 v32, v16, v12, 0
	v_mul_f32_e32 v33, v16, v13
.LBB0_96:
	s_andn2_saveexec_b64 s[42:43], s[42:43]
	s_cbranch_execz .LBB0_98
	s_waitcnt lgkmcnt(1)
	v_lshl_add_u64 v[16:17], s[18:19], 0, v[14:15]
	v_add_co_u32_e32 v10, vcc, 0x8000, v16
	global_load_dword v2, v5, s[14:15]
	s_nop 0
	v_addc_co_u32_e32 v11, vcc, 0, v17, vcc
	global_load_dwordx4 v[6:9], v14, s[18:19] offset:16 nt
	v_lshl_add_u64 v[16:17], v[16:17], 0, s[38:39]
	global_load_dwordx4 v[10:13], v[10:11], off nt
	s_waitcnt lgkmcnt(0)
	global_load_dwordx4 v[16:19], v[16:17], off offset:16 nt
	s_nop 0
	global_load_dword v20, v5, s[12:13]
	global_load_dwordx4 v[36:39], v14, s[18:19] nt
	s_waitcnt vmcnt(4)
	v_mov_b32_e32 v32, v8
	s_waitcnt vmcnt(2)
	v_pk_mul_f32 v[16:17], v[2:3], v[16:17] op_sel_hi:[0,1]
	v_pk_mul_f32 v[10:11], v[2:3], v[10:11] op_sel_hi:[0,1]
	v_pk_mul_f32 v[12:13], v[2:3], v[12:13] op_sel_hi:[0,1]
	v_mov_b32_e32 v33, v18
	v_mov_b32_e32 v18, v9
	s_waitcnt vmcnt(0)
	v_pk_fma_f32 v[8:9], v[20:21], v[36:37], v[10:11] op_sel_hi:[0,1,1]
	v_pk_fma_f32 v[10:11], v[20:21], v[38:39], v[12:13] op_sel_hi:[0,1,1]
	v_pk_fma_f32 v[12:13], v[20:21], v[6:7], v[16:17] op_sel_hi:[0,1,1]
	v_mov_b32_e32 v21, v2
	v_pk_add_f32 v[6:7], v[8:9], 0 op_sel_hi:[1,0]
	v_pk_add_f32 v[8:9], v[10:11], 0 op_sel_hi:[1,0]
	v_pk_mul_f32 v[10:11], v[20:21], v[32:33]
	v_pk_add_f32 v[2:3], v[12:13], 0 op_sel_hi:[1,0]
	v_pk_mul_f32 v[12:13], v[20:21], v[18:19]
	v_add_f32_e32 v5, v10, v11
	v_add_f32_e32 v32, 0, v5
	v_add_f32_e32 v33, v12, v13
.LBB0_98:
	s_or_b64 exec, exec, s[42:43]
	v_add_lshl_u32 v36, v85, v4, 2
	v_or_b32_e32 v4, v28, v34
	v_lshlrev_b32_e32 v14, 5, v4
	s_and_saveexec_b64 s[0:1], s[8:9]
	s_xor_b64 s[42:43], exec, s[0:1]
	s_cbranch_execz .LBB0_100
	v_lshl_add_u64 v[4:5], s[18:19], 0, v[14:15]
	v_add_co_u32_e32 v10, vcc, 0x10000, v4
	s_waitcnt lgkmcnt(1)
	global_load_dword v16, v36, s[16:17] offset:256
	v_addc_co_u32_e32 v11, vcc, 0, v5, vcc
	v_lshl_add_u64 v[4:5], v[4:5], 0, s[34:35]
	global_load_dwordx4 v[10:13], v[10:11], off nt
	s_nop 0
	global_load_dwordx4 v[38:41], v[4:5], off offset:16 nt
	s_waitcnt vmcnt(1)
	v_pk_fma_f32 v[4:5], v[16:17], v[10:11], v[6:7] op_sel_hi:[0,1,1]
	v_pk_fma_f32 v[20:21], v[16:17], v[12:13], v[8:9] op_sel_hi:[0,1,1]
	s_waitcnt vmcnt(0) lgkmcnt(0)
	v_pk_fma_f32 v[18:19], v[16:17], v[38:39], v[2:3] op_sel_hi:[0,1,1]
	v_fmac_f32_e32 v32, v16, v40
	v_mul_f32_e32 v35, v16, v41
.LBB0_100:
	s_andn2_saveexec_b64 s[42:43], s[42:43]
	s_cbranch_execz .LBB0_102
	v_lshl_add_u64 v[20:21], s[18:19], 0, v[14:15]
	s_waitcnt lgkmcnt(1)
	v_add_co_u32_e32 v16, vcc, 0x8000, v20
	global_load_dword v4, v36, s[14:15] offset:256
	s_nop 0
	v_addc_co_u32_e32 v17, vcc, 0, v21, vcc
	s_waitcnt lgkmcnt(0)
	global_load_dwordx4 v[16:19], v[16:17], off nt
	v_lshl_add_u64 v[20:21], v[20:21], 0, s[38:39]
	global_load_dwordx4 v[10:13], v14, s[18:19] offset:16 nt
	global_load_dwordx4 v[38:41], v[20:21], off offset:16 nt
	global_load_dword v46, v36, s[12:13] offset:256
	global_load_dwordx4 v[42:45], v14, s[18:19] nt
	s_waitcnt vmcnt(4)
	v_pk_mul_f32 v[16:17], v[4:5], v[16:17] op_sel_hi:[0,1]
	v_pk_mul_f32 v[18:19], v[4:5], v[18:19] op_sel_hi:[0,1]
	s_waitcnt vmcnt(2)
	v_pk_mul_f32 v[20:21], v[4:5], v[38:39] op_sel_hi:[0,1]
	v_mov_b32_e32 v48, v12
	v_mov_b32_e32 v49, v40
	v_mov_b32_e32 v40, v13
	s_waitcnt vmcnt(0)
	v_pk_fma_f32 v[12:13], v[46:47], v[42:43], v[16:17] op_sel_hi:[0,1,1]
	v_pk_fma_f32 v[16:17], v[46:47], v[44:45], v[18:19] op_sel_hi:[0,1,1]
	v_pk_fma_f32 v[10:11], v[46:47], v[10:11], v[20:21] op_sel_hi:[0,1,1]
	v_mov_b32_e32 v47, v4
	v_pk_add_f32 v[18:19], v[2:3], v[10:11]
	v_pk_mul_f32 v[2:3], v[46:47], v[48:49]
	v_pk_add_f32 v[4:5], v[6:7], v[12:13]
	v_pk_mul_f32 v[6:7], v[46:47], v[40:41]
	v_add_f32_e32 v2, v2, v3
	v_pk_add_f32 v[20:21], v[8:9], v[16:17]
	v_add_f32_e32 v32, v32, v2
	v_add_f32_e32 v35, v6, v7
.LBB0_102:
	s_or_b64 exec, exec, s[42:43]
	v_or_b32_e32 v2, v29, v34
	v_lshlrev_b32_e32 v14, 5, v2
	s_and_saveexec_b64 s[0:1], s[8:9]
	s_xor_b64 s[42:43], exec, s[0:1]
	s_cbranch_execz .LBB0_104
	v_lshl_add_u64 v[2:3], s[18:19], 0, v[14:15]
	v_add_co_u32_e32 v6, vcc, 0x10000, v2
	global_load_dword v10, v36, s[16:17] offset:512
	s_nop 0
	v_addc_co_u32_e32 v7, vcc, 0, v3, vcc
	v_lshl_add_u64 v[2:3], v[2:3], 0, s[34:35]
	s_waitcnt lgkmcnt(4)
	global_load_dwordx4 v[6:9], v[6:7], off nt
	s_nop 0
	global_load_dwordx4 v[38:41], v[2:3], off offset:16 nt
	s_waitcnt vmcnt(1)
	v_pk_fma_f32 v[2:3], v[10:11], v[6:7], v[4:5] op_sel_hi:[0,1,1]
	s_waitcnt lgkmcnt(1)
	v_pk_fma_f32 v[16:17], v[10:11], v[8:9], v[20:21] op_sel_hi:[0,1,1]
	s_waitcnt vmcnt(0) lgkmcnt(0)
	v_pk_fma_f32 v[12:13], v[10:11], v[38:39], v[18:19] op_sel_hi:[0,1,1]
	v_fmac_f32_e32 v32, v10, v40
	v_mul_f32_e32 v37, v10, v41
.LBB0_104:
	s_andn2_saveexec_b64 s[42:43], s[42:43]
	s_cbranch_execz .LBB0_106
	s_waitcnt lgkmcnt(1)
	v_lshl_add_u64 v[16:17], s[18:19], 0, v[14:15]
	v_add_co_u32_e32 v10, vcc, 0x8000, v16
	global_load_dword v2, v36, s[14:15] offset:512
	s_nop 0
	v_addc_co_u32_e32 v11, vcc, 0, v17, vcc
	global_load_dwordx4 v[10:13], v[10:11], off nt
	v_lshl_add_u64 v[16:17], v[16:17], 0, s[38:39]
	global_load_dwordx4 v[6:9], v14, s[18:19] offset:16 nt
	global_load_dwordx4 v[38:41], v[16:17], off offset:16 nt
	global_load_dword v46, v36, s[12:13] offset:512
	global_load_dwordx4 v[42:45], v14, s[18:19] nt
	s_waitcnt vmcnt(4)
	v_pk_mul_f32 v[10:11], v[2:3], v[10:11] op_sel_hi:[0,1]
	v_pk_mul_f32 v[12:13], v[2:3], v[12:13] op_sel_hi:[0,1]
	s_waitcnt vmcnt(2)
	v_pk_mul_f32 v[16:17], v[2:3], v[38:39] op_sel_hi:[0,1]
	v_mov_b32_e32 v48, v8
	v_mov_b32_e32 v49, v40
	v_mov_b32_e32 v40, v9
	s_waitcnt vmcnt(0)
	v_pk_fma_f32 v[8:9], v[46:47], v[42:43], v[10:11] op_sel_hi:[0,1,1]
	v_pk_fma_f32 v[10:11], v[46:47], v[44:45], v[12:13] op_sel_hi:[0,1,1]
	v_pk_fma_f32 v[6:7], v[46:47], v[6:7], v[16:17] op_sel_hi:[0,1,1]
	v_mov_b32_e32 v47, v2
	v_pk_add_f32 v[2:3], v[4:5], v[8:9]
	v_pk_mul_f32 v[4:5], v[46:47], v[48:49]
	s_waitcnt lgkmcnt(0)
	v_pk_add_f32 v[12:13], v[18:19], v[6:7]
	v_pk_mul_f32 v[6:7], v[46:47], v[40:41]
	v_add_f32_e32 v4, v4, v5
	v_pk_add_f32 v[16:17], v[20:21], v[10:11]
	v_add_f32_e32 v32, v32, v4
	v_add_f32_e32 v37, v6, v7
.LBB0_106:
	s_or_b64 exec, exec, s[42:43]
	v_or_b32_e32 v4, v30, v34
	v_lshlrev_b32_e32 v14, 5, v4
	s_and_saveexec_b64 s[0:1], s[8:9]
	s_xor_b64 s[8:9], exec, s[0:1]
	s_cbranch_execz .LBB0_108
	v_lshl_add_u64 v[10:11], s[18:19], 0, v[14:15]
	v_add_co_u32_e32 v4, vcc, 0x10000, v10
	global_load_dword v8, v36, s[16:17] offset:768
	s_nop 0
	v_addc_co_u32_e32 v5, vcc, 0, v11, vcc
	v_lshl_add_u64 v[10:11], v[10:11], 0, s[34:35]
	global_load_dwordx4 v[4:7], v[4:5], off nt
	s_nop 0
	global_load_dwordx4 v[38:41], v[10:11], off offset:16 nt
	s_waitcnt vmcnt(1) lgkmcnt(4)
	v_pk_fma_f32 v[20:21], v[8:9], v[4:5], v[2:3] op_sel_hi:[0,1,1]
	s_waitcnt lgkmcnt(0)
	v_pk_fma_f32 v[18:19], v[8:9], v[6:7], v[16:17] op_sel_hi:[0,1,1]
	s_waitcnt vmcnt(0)
	v_pk_fma_f32 v[10:11], v[8:9], v[38:39], v[12:13] op_sel_hi:[0,1,1]
	v_fmac_f32_e32 v32, v8, v40
	v_mul_f32_e32 v34, v8, v41
.LBB0_108:
	s_andn2_saveexec_b64 s[8:9], s[8:9]
	s_cbranch_execz .LBB0_110
	s_waitcnt lgkmcnt(0)
	v_lshl_add_u64 v[18:19], s[18:19], 0, v[14:15]
	v_add_co_u32_e32 v8, vcc, 0x8000, v18
	global_load_dword v34, v36, s[14:15] offset:768
	s_nop 0
	v_addc_co_u32_e32 v9, vcc, 0, v19, vcc
	global_load_dwordx4 v[8:11], v[8:9], off nt
	v_lshl_add_u64 v[18:19], v[18:19], 0, s[38:39]
	global_load_dwordx4 v[4:7], v14, s[18:19] offset:16 nt
	global_load_dwordx4 v[38:41], v[18:19], off offset:16 nt
	global_load_dword v42, v36, s[12:13] offset:768
	s_nop 0
	global_load_dwordx4 v[18:21], v14, s[18:19] nt
	s_waitcnt vmcnt(4)
	v_pk_mul_f32 v[8:9], v[34:35], v[8:9] op_sel_hi:[0,1]
	v_pk_mul_f32 v[10:11], v[34:35], v[10:11] op_sel_hi:[0,1]
	s_waitcnt vmcnt(2)
	v_pk_mul_f32 v[38:39], v[34:35], v[38:39] op_sel_hi:[0,1]
	v_mov_b32_e32 v44, v6
	v_mov_b32_e32 v45, v40
	v_mov_b32_e32 v40, v7
	s_waitcnt vmcnt(0)
	v_pk_fma_f32 v[6:7], v[42:43], v[18:19], v[8:9] op_sel_hi:[0,1,1]
	v_pk_fma_f32 v[8:9], v[42:43], v[20:21], v[10:11] op_sel_hi:[0,1,1]
	v_pk_fma_f32 v[4:5], v[42:43], v[4:5], v[38:39] op_sel_hi:[0,1,1]
	v_mov_b32_e32 v43, v34
	v_pk_add_f32 v[20:21], v[2:3], v[6:7]
	v_pk_mul_f32 v[2:3], v[42:43], v[44:45]
	v_pk_add_f32 v[10:11], v[12:13], v[4:5]
	v_pk_mul_f32 v[4:5], v[42:43], v[40:41]
	v_add_f32_e32 v2, v2, v3
	v_pk_add_f32 v[18:19], v[16:17], v[8:9]
	v_add_f32_e32 v32, v32, v2
	v_add_f32_e32 v34, v4, v5

.LBB0_887:
	global_load_dwordx4 v[14:17], v[76:77], off nt
	global_load_dwordx4 v[10:13], v[76:77], off offset:1024 nt
	global_load_dwordx4 v[6:9], v[76:77], off offset:2048 nt
	global_load_dwordx4 v[2:5], v[76:77], off offset:3072 nt
	v_add_co_u32_e32 v22, vcc, 0x1000, v76
	global_load_dwordx4 v[42:45], v[72:73], off nt
	s_nop 0
	v_addc_co_u32_e32 v23, vcc, 0, v77, vcc
	v_add_co_u32_e32 v26, vcc, 0x2000, v76
	global_load_dwordx4 v[66:69], v[22:23], off nt
	global_load_dwordx4 v[54:57], v[22:23], off offset:1024 nt
	global_load_dwordx4 v[38:41], v[22:23], off offset:2048 nt
	global_load_dwordx4 v[18:21], v[22:23], off offset:3072 nt
	v_addc_co_u32_e32 v27, vcc, 0, v77, vcc
	v_add_co_u32_e32 v88, vcc, 0x3000, v76
	global_load_dwordx4 v[62:65], v[26:27], off nt
	global_load_dwordx4 v[50:53], v[26:27], off offset:1024 nt
	global_load_dwordx4 v[34:37], v[26:27], off offset:2048 nt
	global_load_dwordx4 v[22:25], v[26:27], off offset:3072 nt
	v_addc_co_u32_e32 v89, vcc, 0, v77, vcc
	global_load_dwordx4 v[58:61], v[88:89], off nt
	global_load_dwordx4 v[46:49], v[88:89], off offset:1024 nt
	global_load_dwordx4 v[30:33], v[88:89], off offset:2048 nt
	global_load_dwordx4 v[26:29], v[88:89], off offset:3072 nt
	v_add_co_u32_e64 v78, s[10:11], s3, v74
	v_add_u32_e32 v70, s20, v70
	s_nop 0
	v_addc_co_u32_e64 v79, s[10:11], 0, v75, s[10:11]
	v_lshl_add_u64 v[76:77], v[76:77], 0, s[42:43]
	s_waitcnt vmcnt(16)
	v_mul_f32_e32 v87, v15, v15
	v_mul_f32_e32 v88, v17, v17
	s_waitcnt vmcnt(15)
	v_mul_f32_e32 v89, v11, v11
	v_mul_f32_e32 v90, v13, v13
	s_waitcnt vmcnt(14)
	v_mul_f32_e32 v91, v7, v7
	v_mul_f32_e32 v92, v9, v9
	s_waitcnt vmcnt(13)
	v_mul_f32_e32 v93, v3, v3
	v_mul_f32_e32 v94, v5, v5
	v_fmac_f32_e32 v87, v14, v14
	v_fmac_f32_e32 v88, v16, v16
	v_fmac_f32_e32 v89, v10, v10
	v_fmac_f32_e32 v90, v12, v12
	v_fmac_f32_e32 v91, v6, v6
	v_fmac_f32_e32 v92, v8, v8
	v_fmac_f32_e32 v93, v2, v2
	v_fmac_f32_e32 v94, v4, v4
	v_add_f32_e32 v87, v87, v88
	v_add_f32_e32 v88, v89, v90
	v_add_f32_e32 v89, v91, v92
	v_add_f32_e32 v90, v93, v94
	s_waitcnt vmcnt(11)
	v_mul_f32_e32 v91, v67, v67
	v_mul_f32_e32 v92, v69, v69
	s_waitcnt vmcnt(10)
	v_mul_f32_e32 v93, v55, v55
	v_mul_f32_e32 v94, v57, v57
	s_waitcnt vmcnt(9)
	v_mul_f32_e32 v95, v39, v39
	v_mul_f32_e32 v96, v41, v41
	s_waitcnt vmcnt(8)
	v_mul_f32_e32 v97, v19, v19
	v_mul_f32_e32 v98, v21, v21
	v_add_f32_e32 v87, v87, v88
	v_fmac_f32_e32 v91, v66, v66
	v_fmac_f32_e32 v92, v68, v68
	v_fmac_f32_e32 v93, v54, v54
	v_fmac_f32_e32 v94, v56, v56
	v_fmac_f32_e32 v95, v38, v38
	v_fmac_f32_e32 v96, v40, v40
	v_fmac_f32_e32 v97, v18, v18
	v_fmac_f32_e32 v98, v20, v20
	s_waitcnt vmcnt(7)
	v_mul_f32_e32 v88, v63, v63
	v_mul_f32_e32 v99, v65, v65
	s_waitcnt vmcnt(6)
	v_mul_f32_e32 v100, v51, v51
	v_mul_f32_e32 v101, v53, v53
	v_add_f32_e32 v87, v87, v89
	s_waitcnt vmcnt(5)
	v_mul_f32_e32 v102, v35, v35
	v_mul_f32_e32 v103, v37, v37
	v_add_f32_e32 v89, v91, v92
	v_add_f32_e32 v91, v93, v94
	v_add_f32_e32 v92, v95, v96
	v_add_f32_e32 v93, v97, v98
	v_fmac_f32_e32 v88, v62, v62
	v_fmac_f32_e32 v99, v64, v64
	v_fmac_f32_e32 v100, v50, v50
	v_fmac_f32_e32 v101, v52, v52
	s_waitcnt vmcnt(3)
	v_mul_f32_e32 v94, v59, v59
	v_mul_f32_e32 v95, v61, v61
	s_waitcnt vmcnt(2)
	v_mul_f32_e32 v96, v47, v47
	v_mul_f32_e32 v97, v49, v49
	v_add_f32_e32 v87, v87, v90
	v_mul_f32_e32 v104, v23, v23
	v_mul_f32_e32 v105, v25, v25
	v_fmac_f32_e32 v102, v34, v34
	v_fmac_f32_e32 v103, v36, v36
	s_waitcnt vmcnt(1)
	v_mul_f32_e32 v98, v31, v31
	v_mul_f32_e32 v106, v33, v33
	v_add_f32_e32 v89, v89, v91
	v_add_f32_e32 v88, v88, v99
	v_add_f32_e32 v90, v100, v101
	v_fmac_f32_e32 v94, v58, v58
	v_fmac_f32_e32 v95, v60, v60
	v_fmac_f32_e32 v96, v46, v46
	v_fmac_f32_e32 v97, v48, v48
	ds_bpermute_b32 v100, v80, v87
	v_fmac_f32_e32 v104, v22, v22
	v_fmac_f32_e32 v105, v24, v24
	s_waitcnt vmcnt(0)
	v_mul_f32_e32 v107, v27, v27
	v_mul_f32_e32 v108, v29, v29
	v_add_f32_e32 v91, v102, v103
	v_fmac_f32_e32 v98, v30, v30
	v_fmac_f32_e32 v106, v32, v32
	v_add_f32_e32 v89, v89, v92
	v_add_f32_e32 v88, v88, v90
	v_add_f32_e32 v90, v94, v95
	v_add_f32_e32 v92, v96, v97
	v_add_f32_e32 v99, v104, v105
	v_fmac_f32_e32 v107, v26, v26
	v_fmac_f32_e32 v108, v28, v28
	v_add_f32_e32 v94, v98, v106
	v_add_f32_e32 v89, v89, v93
	v_add_f32_e32 v88, v88, v91
	v_add_f32_e32 v90, v90, v92
	v_add_f32_e32 v95, v107, v108
	ds_bpermute_b32 v91, v80, v89
	v_add_f32_e32 v88, v88, v99
	v_add_f32_e32 v90, v90, v94
	ds_bpermute_b32 v92, v80, v88
	v_add_f32_e32 v90, v90, v95
	ds_bpermute_b32 v93, v80, v90
	s_waitcnt lgkmcnt(3)
	v_add_f32_e32 v87, v87, v100
	ds_bpermute_b32 v94, v81, v87
	s_waitcnt lgkmcnt(3)
	v_add_f32_e32 v89, v89, v91
	ds_bpermute_b32 v91, v81, v89
	s_waitcnt lgkmcnt(3)
	v_add_f32_e32 v88, v88, v92
	ds_bpermute_b32 v92, v81, v88
	s_waitcnt lgkmcnt(3)
	v_add_f32_e32 v90, v90, v93
	ds_bpermute_b32 v93, v81, v90
	s_waitcnt lgkmcnt(3)
	v_add_f32_e32 v87, v87, v94
	ds_bpermute_b32 v94, v82, v87
	s_waitcnt lgkmcnt(3)
	v_add_f32_e32 v89, v89, v91
	ds_bpermute_b32 v91, v82, v89
	s_waitcnt lgkmcnt(3)
	v_add_f32_e32 v88, v88, v92
	ds_bpermute_b32 v92, v82, v88
	s_waitcnt lgkmcnt(3)
	v_add_f32_e32 v90, v90, v93
	ds_bpermute_b32 v93, v82, v90
	s_waitcnt lgkmcnt(3)
	v_add_f32_e32 v87, v87, v94
	ds_bpermute_b32 v94, v83, v87
	s_waitcnt lgkmcnt(3)
	v_add_f32_e32 v89, v89, v91
	ds_bpermute_b32 v91, v83, v89
	s_waitcnt lgkmcnt(3)
	v_add_f32_e32 v88, v88, v92
	ds_bpermute_b32 v92, v83, v88
	s_waitcnt lgkmcnt(3)
	v_add_f32_e32 v90, v90, v93
	ds_bpermute_b32 v93, v83, v90
	s_waitcnt lgkmcnt(3)
	v_add_f32_e32 v87, v87, v94
	ds_bpermute_b32 v94, v84, v87
	s_waitcnt lgkmcnt(3)
	v_add_f32_e32 v89, v89, v91
	ds_bpermute_b32 v91, v84, v89
	s_waitcnt lgkmcnt(3)
	v_add_f32_e32 v88, v88, v92
	ds_bpermute_b32 v92, v84, v88
	s_waitcnt lgkmcnt(3)
	v_add_f32_e32 v90, v90, v93
	ds_bpermute_b32 v93, v84, v90
	s_waitcnt lgkmcnt(3)
	v_add_f32_e32 v87, v87, v94
	ds_bpermute_b32 v94, v85, v87
	s_waitcnt lgkmcnt(3)
	v_add_f32_e32 v89, v89, v91
	ds_bpermute_b32 v91, v85, v89
	s_waitcnt lgkmcnt(3)
	v_add_f32_e32 v88, v88, v92
	ds_bpermute_b32 v92, v85, v88
	s_waitcnt lgkmcnt(3)
	v_add_f32_e32 v90, v90, v93
	ds_bpermute_b32 v93, v85, v90
	s_waitcnt lgkmcnt(3)
	v_add_f32_e32 v87, v87, v94
	v_fmamk_f32 v87, v87, 0x3a800000, v71
	v_mul_f32_e32 v94, 0x4f800000, v87
	v_cmp_gt_f32_e32 vcc, s4, v87
	s_waitcnt lgkmcnt(2)
	v_add_f32_e32 v89, v89, v91
	v_fmamk_f32 v89, v89, 0x3a800000, v71
	v_cndmask_b32_e32 v87, v87, v94, vcc
	s_waitcnt lgkmcnt(1)
	v_add_f32_e32 v88, v88, v92
	v_sqrt_f32_e32 v91, v87
	v_mul_f32_e32 v92, 0x4f800000, v89
	v_fmamk_f32 v88, v88, 0x3a800000, v71
	s_waitcnt lgkmcnt(0)
	v_add_f32_e32 v90, v90, v93
	v_cmp_gt_f32_e64 s[10:11], s4, v89
	v_cmp_gt_f32_e64 s[12:13], s4, v88
	v_fmamk_f32 v90, v90, 0x3a800000, v71
	v_cndmask_b32_e64 v89, v89, v92, s[10:11]
	v_mul_f32_e32 v92, 0x4f800000, v88
	v_sqrt_f32_e32 v93, v89
	v_cndmask_b32_e64 v88, v88, v92, s[12:13]
	v_mul_f32_e32 v92, 0x4f800000, v90
	v_cmp_gt_f32_e64 s[14:15], s4, v90
	v_sqrt_f32_e32 v94, v88
	v_add_u32_e32 v95, 1, v91
	v_cndmask_b32_e64 v90, v90, v92, s[14:15]
	v_add_u32_e32 v92, -1, v91
	v_fma_f32 v97, -v92, v91, v87
	v_fma_f32 v98, -v95, v91, v87
	v_cmp_ge_f32_e64 s[16:17], 0, v97
	v_sqrt_f32_e32 v96, v90
	v_add_u32_e32 v97, 1, v93
	v_cndmask_b32_e64 v91, v91, v92, s[16:17]
	v_add_u32_e32 v92, -1, v93
	v_cmp_lt_f32_e64 s[16:17], 0, v98
	v_add_u32_e32 v99, -1, v94
	v_fma_f32 v98, -v97, v93, v89
	v_cndmask_b32_e64 v91, v91, v95, s[16:17]
	v_fma_f32 v95, -v92, v93, v89
	v_cmp_ge_f32_e64 s[16:17], 0, v95
	v_add_u32_e32 v100, 1, v94
	v_mul_f32_e32 v101, 0x37800000, v91
	v_cndmask_b32_e64 v92, v93, v92, s[16:17]
	v_fma_f32 v93, -v99, v94, v88
	v_cmp_lt_f32_e64 s[16:17], 0, v98
	v_fma_f32 v95, -v100, v94, v88
	v_add_u32_e32 v98, -1, v96
	v_cndmask_b32_e32 v91, v91, v101, vcc
	v_cmp_ge_f32_e32 vcc, 0, v93
	v_add_u32_e32 v102, 1, v96
	v_cndmask_b32_e64 v92, v92, v97, s[16:17]
	v_cndmask_b32_e32 v93, v94, v99, vcc
	v_cmp_lt_f32_e32 vcc, 0, v95
	v_fma_f32 v94, -v98, v96, v90
	v_fma_f32 v95, -v102, v96, v90
	v_cmp_class_f32_e64 s[16:17], v87, v86
	v_cndmask_b32_e32 v93, v93, v100, vcc
	v_cmp_ge_f32_e32 vcc, 0, v94
	v_cndmask_b32_e64 v87, v91, v87, s[16:17]
	v_mul_f32_e32 v91, 0x37800000, v92
	v_cndmask_b32_e32 v94, v96, v98, vcc
	v_cmp_lt_f32_e32 vcc, 0, v95
	v_div_scale_f32 v95, s[0:1], v87, v87, 1.0
	v_cndmask_b32_e64 v91, v92, v91, s[10:11]
	v_cmp_class_f32_e64 s[10:11], v89, v86
	v_mul_f32_e32 v92, 0x37800000, v93
	v_cndmask_b32_e32 v94, v94, v102, vcc
	v_rcp_f32_e32 v97, v95
	v_cndmask_b32_e64 v89, v91, v89, s[10:11]
	v_cndmask_b32_e64 v91, v93, v92, s[12:13]
	v_cmp_class_f32_e32 vcc, v88, v86
	v_mul_f32_e32 v92, 0x37800000, v94
	v_div_scale_f32 v93, s[0:1], v89, v89, 1.0
	v_cndmask_b32_e32 v88, v91, v88, vcc
	v_cndmask_b32_e64 v91, v94, v92, s[14:15]
	v_cmp_class_f32_e32 vcc, v90, v86
	v_rcp_f32_e32 v92, v93
	v_div_scale_f32 v94, s[0:1], v88, v88, 1.0
	v_cndmask_b32_e32 v90, v91, v90, vcc
	v_rcp_f32_e32 v91, v94
	v_div_scale_f32 v100, s[0:1], v90, v90, 1.0
	v_fma_f32 v102, -v95, v97, 1.0
	v_rcp_f32_e32 v103, v100
	v_div_scale_f32 v96, s[16:17], 1.0, v87, 1.0
	v_fmac_f32_e32 v97, v102, v97
	v_mul_f32_e32 v102, v96, v97
	v_fma_f32 v104, -v93, v92, 1.0
	v_div_scale_f32 v98, s[10:11], 1.0, v89, 1.0
	v_fma_f32 v105, -v95, v102, v96
	v_fmac_f32_e32 v92, v104, v92
	v_fma_f32 v104, -v94, v91, 1.0
	v_div_scale_f32 v99, s[12:13], 1.0, v88, 1.0
	v_fmac_f32_e32 v102, v105, v97
	v_mul_f32_e32 v105, v98, v92
	v_fmac_f32_e32 v91, v104, v91
	v_fma_f32 v104, -v100, v103, 1.0
	v_div_scale_f32 v101, s[14:15], 1.0, v90, 1.0
	v_fma_f32 v95, -v95, v102, v96
	v_fma_f32 v96, -v93, v105, v98
	v_mul_f32_e32 v106, v99, v91
	v_fmac_f32_e32 v103, v104, v103
	s_mov_b64 vcc, s[16:17]
	v_div_fmas_f32 v95, v95, v97, v102
	v_fmac_f32_e32 v105, v96, v92
	v_fma_f32 v96, -v94, v106, v99
	v_mul_f32_e32 v97, v101, v103
	v_div_fixup_f32 v87, v95, v87, 1.0
	v_fma_f32 v93, -v93, v105, v98
	v_fmac_f32_e32 v106, v96, v91
	v_fma_f32 v95, -v100, v97, v101
	s_mov_b64 vcc, s[10:11]
	v_div_fmas_f32 v92, v93, v92, v105
	v_fma_f32 v93, -v94, v106, v99
	v_fmac_f32_e32 v97, v95, v103
	v_mul_f32_e32 v14, v14, v87
	v_mul_f32_e32 v15, v15, v87
	s_mov_b64 vcc, s[12:13]
	v_mul_f32_e32 v16, v16, v87
	v_mul_f32_e32 v17, v17, v87
	v_mul_f32_e32 v94, v10, v87
	v_mul_f32_e32 v95, v11, v87
	v_mul_f32_e32 v96, v12, v87
	v_mul_f32_e32 v98, v13, v87
	v_div_fixup_f32 v89, v92, v89, 1.0
	v_div_fmas_f32 v10, v93, v91, v106
	v_fma_f32 v11, -v100, v97, v101
	v_mul_f32_e32 v12, v14, v42
	v_mul_f32_e32 v13, v15, v43
	s_mov_b64 vcc, s[14:15]
	v_mul_f32_e32 v14, v16, v44
	v_mul_f32_e32 v15, v17, v45
	v_div_fixup_f32 v16, v10, v88, 1.0
	v_div_fmas_f32 v17, v11, v103, v97
	v_cvt_pk_bf16_f32 v10, v12, v13
	v_cvt_pk_bf16_f32 v11, v14, v15
	v_mul_f32_e32 v12, v66, v89
	v_mul_f32_e32 v13, v67, v89
	v_mul_f32_e32 v14, v68, v89
	v_mul_f32_e32 v15, v69, v89
	global_store_dwordx2 v[74:75], v[10:11], off
	v_mul_f32_e32 v10, v12, v42
	v_mul_f32_e32 v11, v13, v43
	v_div_fixup_f32 v17, v17, v90, 1.0
	v_mul_f32_e32 v12, v14, v44
	v_mul_f32_e32 v13, v15, v45
	v_mul_f32_e32 v14, v62, v16
	v_mul_f32_e32 v15, v63, v16
	v_mul_f32_e32 v62, v64, v16
	v_mul_f32_e32 v63, v65, v16
	v_cvt_pk_bf16_f32 v10, v10, v11
	v_cvt_pk_bf16_f32 v11, v12, v13
	v_mul_f32_e32 v12, v14, v42
	v_mul_f32_e32 v13, v15, v43
	v_mul_f32_e32 v14, v62, v44
	v_mul_f32_e32 v15, v63, v45
	v_mul_f32_e32 v58, v58, v17
	v_mul_f32_e32 v59, v59, v17
	v_mul_f32_e32 v60, v60, v17
	v_mul_f32_e32 v61, v61, v17
	global_store_dwordx2 v[74:75], v[10:11], off offset:2048
	v_cvt_pk_bf16_f32 v10, v12, v13
	v_cvt_pk_bf16_f32 v11, v14, v15
	v_mul_f32_e32 v12, v42, v58
	v_mul_f32_e32 v13, v43, v59
	v_mul_f32_e32 v14, v44, v60
	v_mul_f32_e32 v15, v45, v61
	global_store_dwordx2 v[78:79], v[10:11], off
	v_cvt_pk_bf16_f32 v10, v12, v13
	v_cvt_pk_bf16_f32 v11, v14, v15
	global_store_dwordx2 v[78:79], v[10:11], off offset:2048
	global_load_dwordx4 v[10:13], v[72:73], off offset:1024 nt
	v_mul_f32_e32 v14, v54, v89
	v_mul_f32_e32 v15, v55, v89
	v_mul_f32_e32 v44, v50, v16
	v_mul_f32_e32 v45, v51, v16
	v_mul_f32_e32 v46, v46, v17
	v_mul_f32_e32 v47, v47, v17
	v_mul_f32_e32 v42, v56, v89
	v_mul_f32_e32 v43, v57, v89
	v_mul_f32_e32 v50, v52, v16
	v_mul_f32_e32 v51, v53, v16
	v_mul_f32_e32 v48, v48, v17
	v_mul_f32_e32 v49, v49, v17
	v_mul_f32_e32 v6, v6, v87
	v_mul_f32_e32 v7, v7, v87
	v_mul_f32_e32 v8, v8, v87
	v_mul_f32_e32 v9, v9, v87
	v_mul_f32_e32 v34, v34, v16
	v_mul_f32_e32 v35, v35, v16
	v_mul_f32_e32 v36, v36, v16
	v_mul_f32_e32 v37, v37, v16
	v_mul_f32_e32 v30, v30, v17
	v_mul_f32_e32 v31, v31, v17
	v_mul_f32_e32 v32, v32, v17
	v_mul_f32_e32 v33, v33, v17
	v_mul_f32_e32 v2, v2, v87
	v_mul_f32_e32 v3, v3, v87
	v_mul_f32_e32 v4, v4, v87
	v_mul_f32_e32 v5, v5, v87
	v_cmp_lt_i32_e32 vcc, s5, v70
	s_or_b64 s[44:45], vcc, s[44:45]
	s_waitcnt vmcnt(0)
	v_mul_f32_e32 v52, v94, v10
	v_mul_f32_e32 v53, v95, v11
	v_mul_f32_e32 v54, v96, v12
	v_mul_f32_e32 v55, v98, v13
	v_mul_f32_e32 v14, v14, v10
	v_mul_f32_e32 v15, v15, v11
	v_mul_f32_e32 v44, v44, v10
	v_mul_f32_e32 v45, v45, v11
	v_mul_f32_e32 v46, v46, v10
	v_mul_f32_e32 v47, v47, v11
	v_cvt_pk_bf16_f32 v10, v52, v53
	v_cvt_pk_bf16_f32 v11, v54, v55
	v_mul_f32_e32 v42, v42, v12
	v_mul_f32_e32 v43, v43, v13
	global_store_dwordx2 v[74:75], v[10:11], off offset:512
	v_cvt_pk_bf16_f32 v10, v14, v15
	v_cvt_pk_bf16_f32 v11, v42, v43
	v_mul_f32_e32 v50, v50, v12
	v_mul_f32_e32 v51, v51, v13
	global_store_dwordx2 v[74:75], v[10:11], off offset:2560
	v_cvt_pk_bf16_f32 v10, v44, v45
	v_cvt_pk_bf16_f32 v11, v50, v51
	v_mul_f32_e32 v12, v48, v12
	v_mul_f32_e32 v13, v49, v13
	global_store_dwordx2 v[78:79], v[10:11], off offset:512
	v_cvt_pk_bf16_f32 v10, v46, v47
	v_cvt_pk_bf16_f32 v11, v12, v13
	global_store_dwordx2 v[78:79], v[10:11], off offset:2560
	global_load_dwordx4 v[10:13], v[72:73], off offset:2048 nt
	v_mul_f32_e32 v14, v38, v89
	v_mul_f32_e32 v15, v39, v89
	v_mul_f32_e32 v38, v40, v89
	v_mul_f32_e32 v39, v41, v89
	s_waitcnt vmcnt(0)
	v_mul_f32_e32 v6, v6, v10
	v_mul_f32_e32 v7, v7, v11
	v_mul_f32_e32 v8, v8, v12
	v_mul_f32_e32 v9, v9, v13
	v_cvt_pk_bf16_f32 v6, v6, v7
	v_cvt_pk_bf16_f32 v7, v8, v9
	v_mul_f32_e32 v14, v14, v10
	v_mul_f32_e32 v15, v15, v11
	v_mul_f32_e32 v38, v38, v12
	v_mul_f32_e32 v39, v39, v13
	global_store_dwordx2 v[74:75], v[6:7], off offset:1024
	v_cvt_pk_bf16_f32 v6, v14, v15
	v_cvt_pk_bf16_f32 v7, v38, v39
	v_mul_f32_e32 v34, v34, v10
	v_mul_f32_e32 v35, v35, v11
	v_mul_f32_e32 v36, v36, v12
	v_mul_f32_e32 v37, v37, v13
	global_store_dwordx2 v[74:75], v[6:7], off offset:3072
	v_cvt_pk_bf16_f32 v6, v34, v35
	v_cvt_pk_bf16_f32 v7, v36, v37
	v_mul_f32_e32 v10, v30, v10
	v_mul_f32_e32 v11, v31, v11
	v_mul_f32_e32 v12, v32, v12
	v_mul_f32_e32 v13, v33, v13
	global_store_dwordx2 v[78:79], v[6:7], off offset:1024
	v_cvt_pk_bf16_f32 v6, v10, v11
	v_cvt_pk_bf16_f32 v7, v12, v13
	global_store_dwordx2 v[78:79], v[6:7], off offset:3072
	global_load_dwordx4 v[6:9], v[72:73], off offset:3072 nt
	v_mul_f32_e32 v10, v18, v89
	v_mul_f32_e32 v11, v19, v89
	v_mul_f32_e32 v12, v20, v89
	v_mul_f32_e32 v13, v21, v89
	v_mul_f32_e32 v14, v22, v16
	v_mul_f32_e32 v15, v23, v16
	v_mul_f32_e32 v18, v24, v16
	v_mul_f32_e32 v16, v25, v16
	v_mul_f32_e32 v19, v26, v17
	v_mul_f32_e32 v20, v27, v17
	v_mul_f32_e32 v21, v28, v17
	v_mul_f32_e32 v17, v29, v17
	s_waitcnt vmcnt(0)
	v_mul_f32_e32 v2, v2, v6
	v_mul_f32_e32 v3, v3, v7
	v_mul_f32_e32 v4, v4, v8
	v_mul_f32_e32 v5, v5, v9
	v_cvt_pk_bf16_f32 v2, v2, v3
	v_cvt_pk_bf16_f32 v3, v4, v5
	v_mul_f32_e32 v10, v10, v6
	v_mul_f32_e32 v11, v11, v7
	v_mul_f32_e32 v12, v12, v8
	v_mul_f32_e32 v13, v13, v9
	global_store_dwordx2 v[74:75], v[2:3], off offset:1536
	v_cvt_pk_bf16_f32 v2, v10, v11
	v_cvt_pk_bf16_f32 v3, v12, v13
	v_mul_f32_e32 v14, v14, v6
	v_mul_f32_e32 v15, v15, v7
	v_mul_f32_e32 v18, v18, v8
	v_mul_f32_e32 v16, v16, v9
	global_store_dwordx2 v[74:75], v[2:3], off offset:3584
	v_cvt_pk_bf16_f32 v2, v14, v15
	v_cvt_pk_bf16_f32 v3, v18, v16
	v_lshl_add_u64 v[74:75], v[74:75], 0, s[22:23]
	v_mul_f32_e32 v6, v19, v6
	v_mul_f32_e32 v7, v20, v7
	v_mul_f32_e32 v8, v21, v8
	v_mul_f32_e32 v9, v17, v9
	global_store_dwordx2 v[78:79], v[2:3], off offset:1536
	v_cvt_pk_bf16_f32 v2, v6, v7
	v_cvt_pk_bf16_f32 v3, v8, v9
	global_store_dwordx2 v[78:79], v[2:3], off offset:3584
	s_andn2_b64 exec, exec, s[44:45]
	s_cbranch_execnz .LBB0_887
